# attention: rescale paths moved out of line (ordinary steps fall through instead of taking a branch)
# baseline (speedup 1.0000x reference)
.LBB0_999:
	v_mfma_f32_32x32x16_bf16 v[4:19], v[80:83], v[180:183], v[4:19]
	global_load_lds_dwordx4 v190, s[48:49]
	s_cselect_b32 s49, s49, s51
	s_cselect_b32 s48, s48, s50
	s_cselect_b32 s43, s38, s40
	s_add_i32 m0, s21, s43
	s_add_i32 s43, s23, s40
	global_load_lds_dwordx4 v192, s[48:49]
	s_add_i32 m0, s43, 0xd000
	s_mov_b32 s43, s39
	global_load_lds_dwordx4 v194, s[50:51]
	s_mov_b32 s39, s44
	s_mov_b32 s44, s15
	s_mov_b32 s45, s14
	v_max3_f32 v2, v52, v36, v53
	s_nop 0
	v_max3_f32 v2, v2, v37, v54
	v_mfma_f32_32x32x16_bf16 v[20:35], v[80:83], v[164:167], v[20:35]
	s_nop 0
	v_max3_f32 v2, v2, v38, v55
	s_nop 0
	v_max3_f32 v2, v2, v39, v56
	v_max3_f32 v68, v60, v44, v61
	v_max3_f32 v2, v2, v40, v57
	v_mfma_f32_32x32x16_bf16 v[4:19], v[76:79], v[176:179], v[4:19]
	s_nop 0
	v_max3_f32 v68, v68, v45, v62
	v_max3_f32 v2, v2, v41, v58
	s_nop 0
	v_max3_f32 v68, v68, v46, v63
	v_max3_f32 v68, v68, v47, v64
	v_mfma_f32_32x32x16_bf16 v[20:35], v[76:79], v[156:159], v[20:35]
	v_max3_f32 v2, v2, v42, v59
	v_max3_f32 v68, v68, v48, v65
	s_nop 0
	v_max3_f32 v68, v68, v49, v66
	v_max3_f32 v68, v68, v50, v67
	s_nop 0
	v_mfma_f32_32x32x16_bf16 v[20:35], v[72:75], v[152:155], v[20:35]
	v_max3_f32 v2, v2, v43, v68
	s_nop 0
	v_max3_f32 v2, v2, v51, v2
	s_nop 0
	v_mov_b32_e32 v69, v2
	v_mfma_f32_32x32x16_bf16 v[4:19], v[72:75], v[148:151], v[4:19]
	s_nop 1
	v_permlane32_swap_b32_e32 v2, v69
	v_max3_f32 v2, v2, v69, v2
	s_nop 0
	v_cmp_lt_f32_e32 vcc, s56, v2
	s_cbranch_vccnz .Lrare_A
	v_mov_b32_e32 v180, v210
.LBB0_1004:
	v_mfma_f32_32x32x16_bf16 v[68:83], v[246:249], v[250:253], 0
	v_mfma_f32_32x32x16_bf16 v[84:99], v[132:135], v[100:103], v[68:83]
	v_mfma_f32_32x32x16_bf16 v[68:83], v[136:139], v[100:103], v[68:83]
	v_add_u32_e32 v2, s45, v189
	ds_read_b128 v[184:187], v2 offset:96
	ds_read_b128 v[210:213], v2 offset:128
	ds_read_b128 v[214:217], v2 offset:6752
	ds_read_b128 v[218:221], v2 offset:160
	ds_read_b128 v[222:225], v2 offset:6784
	ds_read_b128 v[226:229], v2 offset:6816
	v_add_u32_e32 v2, s39, v200
	ds_read_b128 v[176:179], v2 offset:53248
	ds_read_b128 v[164:167], v2 offset:53280
	ds_read_b128 v[230:233], v2 offset:57856
	ds_read_b128 v[238:241], v2 offset:57888
	ds_read_b128 v[160:163], v2 offset:53312
	ds_read_b128 v[156:159], v2 offset:53344
	ds_read_b128 v[242:245], v2 offset:57920
	ds_read_b128 v[152:155], v2 offset:57952
	v_exp_f32_e32 v52, v52
	v_exp_f32_e32 v183, v36
	v_exp_f32_e32 v132, v53
	v_exp_f32_e32 v53, v54
	v_mfma_f32_32x32x16_bf16 v[68:83], v[144:147], v[104:107], v[68:83]
	v_exp_f32_e32 v54, v38
	v_exp_f32_e32 v36, v55
	v_exp_f32_e32 v55, v56
	v_exp_f32_e32 v56, v40
	v_mfma_f32_32x32x16_bf16 v[84:99], v[128:131], v[104:107], v[84:99]
	v_exp_f32_e32 v40, v39
	v_exp_f32_e32 v38, v57
	v_exp_f32_e32 v57, v58
	v_exp_f32_e32 v58, v41
	v_mfma_f32_32x32x16_bf16 v[68:83], v[140:143], v[108:111], v[68:83]
	v_add_u32_e32 v181, s44, v189
	ds_read_b128 v[144:147], v181
	ds_read_b128 v[172:175], v181 offset:32
	ds_read_b128 v[136:139], v181 offset:6656
	ds_read_b128 v[168:171], v181 offset:64
	ds_read_b128 v[148:151], v181 offset:6688
	ds_read_b128 v[140:143], v181 offset:6720
	v_exp_f32_e32 v2, v37
	v_mfma_f32_32x32x16_bf16 v[84:99], v[124:127], v[108:111], v[84:99]
	v_exp_f32_e32 v124, v59
	v_exp_f32_e32 v41, v60
	v_add_f32_e32 v133, v52, v183
	v_add_f32_e32 v37, v53, v54
	s_waitcnt lgkmcnt(14)
	v_mfma_f32_32x32x16_bf16 v[68:83], v[214:217], v[112:115], v[68:83]
	v_exp_f32_e32 v214, v42
	v_exp_f32_e32 v59, v44
	v_exp_f32_e32 v60, v43
	v_exp_f32_e32 v126, v61
	v_mfma_f32_32x32x16_bf16 v[84:99], v[184:187], v[112:115], v[84:99]
	v_exp_f32_e32 v61, v62
	v_exp_f32_e32 v62, v45
	v_exp_f32_e32 v128, v63
	v_exp_f32_e32 v63, v64
	v_mfma_f32_32x32x16_bf16 v[68:83], v[222:225], v[116:119], v[68:83]
	v_exp_f32_e32 v216, v48
	v_exp_f32_e32 v64, v47
	v_exp_f32_e32 v130, v65
	v_mfma_f32_32x32x16_bf16 v[84:99], v[210:213], v[116:119], v[84:99]
	v_exp_f32_e32 v65, v66
	v_exp_f32_e32 v215, v46
	v_exp_f32_e32 v185, v50
	v_mfma_f32_32x32x16_bf16 v[68:83], v[226:229], v[120:123], v[68:83]
	v_exp_f32_e32 v66, v49
	v_exp_f32_e32 v134, v67
	v_add_f32_e32 v39, v55, v56
	v_add_f32_e32 v125, v57, v214
	v_mfma_f32_32x32x16_bf16 v[84:99], v[218:221], v[120:123], v[84:99]
	v_add_f32_e32 v127, v41, v59
	v_add_f32_e32 v129, v61, v215
	v_add_f32_e32 v131, v63, v216
	v_add_f32_e32 v135, v65, v185
	v_exp_f32_e32 v184, v51
	v_cvt_pk_bf16_f32 v42, v52, v132
	v_cvt_pk_bf16_f32 v43, v53, v36
	v_cvt_pk_bf16_f32 v44, v55, v38
	v_cvt_pk_bf16_f32 v45, v57, v124
	v_cvt_pk_bf16_f32 v46, v41, v126
	v_cvt_pk_bf16_f32 v47, v61, v128
	s_waitcnt lgkmcnt(11)
	v_mfma_f32_32x32x16_bf16 v[4:19], v[42:45], v[230:233], v[4:19]
	v_cvt_pk_bf16_f32 v48, v63, v130
	v_cvt_pk_bf16_f32 v49, v65, v134
	v_cvt_pk_bf16_f32 v50, v183, v2
	v_cvt_pk_bf16_f32 v51, v54, v40
	v_cvt_pk_bf16_f32 v52, v56, v58
	v_cvt_pk_bf16_f32 v53, v214, v60
	v_mfma_f32_32x32x16_bf16 v[20:35], v[42:45], v[176:179], v[20:35]
	v_cvt_pk_bf16_f32 v54, v59, v62
	v_cvt_pk_bf16_f32 v55, v215, v64
	v_cvt_pk_bf16_f32 v56, v216, v66
	v_cvt_pk_bf16_f32 v57, v185, v184
	s_add_i32 s14, s46, 5
	s_min_u32 s14, s14, s37
	s_add_i32 s15, s46, 3
	s_min_u32 s46, s15, s37
	s_mulk_i32 s14, 0x3000
	s_add_u32 s14, s10, s14
	s_addc_u32 s15, s11, 0
	s_lshl_b32 s46, s46, 13
	s_add_u32 s46, s12, s46
	s_addc_u32 s47, s13, 0
	s_add_i32 m0, s22, s45
	s_and_b64 s[48:49], s[4:5], exec
	s_waitcnt vmcnt(3) lgkmcnt(0)
	s_barrier
	v_mfma_f32_32x32x16_bf16 v[4:19], v[46:49], v[238:241], v[4:19]
	global_load_lds_dwordx4 v190, s[14:15]
	s_cselect_b32 s15, s15, s47
	s_cselect_b32 s14, s14, s46
	s_cselect_b32 s98, s45, s39
	s_add_i32 m0, s21, s98
	s_add_i32 s98, s23, s39
	global_load_lds_dwordx4 v192, s[14:15]
	s_add_i32 m0, s98, 0xd000
	s_nop 0
	global_load_lds_dwordx4 v194, s[46:47]
	v_max3_f32 v41, v84, v68, v85
	v_max3_f32 v59, v92, v76, v93
	v_add_f32_e32 v132, v132, v2
	v_max3_f32 v41, v41, v69, v86
	v_max3_f32 v59, v59, v77, v94
	v_mfma_f32_32x32x16_bf16 v[20:35], v[46:49], v[164:167], v[20:35]
	s_nop 0
	v_max3_f32 v41, v41, v70, v87
	v_max3_f32 v41, v41, v71, v88
	v_max3_f32 v59, v59, v78, v95
	v_max3_f32 v41, v41, v72, v89
	v_max3_f32 v59, v59, v79, v96
	s_nop 0
	v_max3_f32 v41, v41, v73, v90
	v_max3_f32 v183, v41, v74, v91
	v_mfma_f32_32x32x16_bf16 v[4:19], v[50:53], v[242:245], v[4:19]
	v_add_f32_e32 v41, v132, v133
	v_max3_f32 v59, v59, v80, v97
	v_add_f32_e64 v36, v36, v40
	v_add_f32_e64 v37, v37, v41
	v_max3_f32 v59, v59, v81, v98
	v_max3_f32 v186, v59, v82, v99
	v_add_f32_e32 v59, v36, v37
	v_add_f32_e32 v36, v38, v58
	v_add_f32_e32 v37, v39, v59
	v_mfma_f32_32x32x16_bf16 v[20:35], v[50:53], v[160:163], v[20:35]
	v_add_f32_e32 v61, v36, v37
	v_add_f32_e32 v36, v124, v60
	v_add_f32_e32 v37, v125, v61
	v_add_f32_e32 v63, v36, v37
	v_add_f32_e32 v36, v126, v62
	v_add_f32_e32 v37, v127, v63
	v_add_f32_e32 v65, v36, v37
	v_add_f32_e32 v36, v128, v64
	v_add_f32_e32 v37, v129, v65
	v_mfma_f32_32x32x16_bf16 v[20:35], v[54:57], v[156:159], v[20:35]
	v_add_f32_e32 v67, v36, v37
	v_add_f32_e32 v36, v130, v66
	v_add_f32_e32 v37, v131, v67
	v_add_f32_e32 v185, v36, v37
	v_add_f32_e32 v36, v134, v184
	v_add_f32_e32 v37, v135, v185
	v_add_f32_e32 v2, v36, v37
	v_max3_f32 v36, v183, v75, v186
	v_add_f32_e32 v2, v209, v2
	v_mfma_f32_32x32x16_bf16 v[4:19], v[54:57], v[152:155], v[4:19]
	v_max3_f32 v36, v36, v83, v36
	s_nop 0
	v_mov_b32_e32 v38, v36
	s_nop 0
	s_nop 0
	v_permlane32_swap_b32_e32 v36, v38
	v_max3_f32 v36, v36, v38, v36
	s_nop 0
	v_cmp_lt_f32_e32 vcc, s56, v36
	s_cbranch_vccnz .Lrare_B
	v_mov_b32_e32 v210, v180

.Lrare_A:
	v_add_f32_e32 v180, v210, v2
	v_cvt_pk_bf16_f32 v180, v180, v180
	v_lshlrev_b32_e32 v180, 16, v180
	v_cndmask_b32_e32 v180, v210, v180, vcc
	v_sub_f32_e32 v2, v210, v180
	v_sub_f32_e32 v84, v180, v210
	v_xor_b32_e32 v250, 0x80000000, v180
	v_min_f32_e32 v2, 0, v2
	v_lshrrev_b32_e32 v250, 16, v250
	v_exp_f32_e32 v2, v2
	v_cndmask_b32_e64 v250, 0, v250, s[2:3]
	s_and_saveexec_b64 s[14:15], s[2:3]
	ds_write_b32 v202, v2
	s_or_b64 exec, exec, s[14:15]
	ds_read_b32 v68, v1
	ds_read_b32 v69, v1 offset:4
	ds_read_b32 v70, v1 offset:8
	ds_read_b32 v71, v1 offset:12
	ds_read_b32 v72, v1 offset:32
	ds_read_b32 v73, v1 offset:36
	ds_read_b32 v74, v1 offset:40
	ds_read_b32 v75, v1 offset:44
	ds_read_b32 v76, v1 offset:64
	ds_read_b32 v77, v1 offset:68
	ds_read_b32 v78, v1 offset:72
	ds_read_b32 v79, v1 offset:76
	ds_read_b32 v80, v1 offset:96
	ds_read_b32 v81, v1 offset:100
	ds_read_b32 v82, v1 offset:104
	ds_read_b32 v83, v1 offset:108
	v_mul_f32_e32 v209, v209, v2
	s_waitcnt lgkmcnt(0)
	v_pk_mul_f32 v[20:21], v[20:21], v[68:69]
	v_pk_mul_f32 v[22:23], v[22:23], v[70:71]
	v_pk_mul_f32 v[24:25], v[24:25], v[72:73]
	v_pk_mul_f32 v[26:27], v[26:27], v[74:75]
	v_pk_mul_f32 v[28:29], v[28:29], v[76:77]
	v_pk_mul_f32 v[30:31], v[30:31], v[78:79]
	v_pk_mul_f32 v[32:33], v[32:33], v[80:81]
	v_pk_mul_f32 v[34:35], v[34:35], v[82:83]
	v_pk_mul_f32 v[4:5], v[4:5], v[68:69]
	v_pk_mul_f32 v[6:7], v[6:7], v[70:71]
	v_pk_mul_f32 v[8:9], v[8:9], v[72:73]
	v_pk_mul_f32 v[10:11], v[10:11], v[74:75]
	v_pk_mul_f32 v[12:13], v[12:13], v[76:77]
	v_pk_mul_f32 v[14:15], v[14:15], v[78:79]
	v_pk_mul_f32 v[16:17], v[16:17], v[80:81]
	v_pk_mul_f32 v[18:19], v[18:19], v[82:83]
	v_sub_f32_e32 v36, v36, v84
	v_sub_f32_e32 v37, v37, v84
	v_sub_f32_e32 v38, v38, v84
	v_sub_f32_e32 v39, v39, v84
	v_sub_f32_e32 v40, v40, v84
	v_sub_f32_e32 v41, v41, v84
	v_sub_f32_e32 v42, v42, v84
	v_sub_f32_e32 v43, v43, v84
	v_sub_f32_e32 v44, v44, v84
	v_sub_f32_e32 v45, v45, v84
	v_sub_f32_e32 v46, v46, v84
	v_sub_f32_e32 v47, v47, v84
	v_sub_f32_e32 v48, v48, v84
	v_sub_f32_e32 v49, v49, v84
	v_sub_f32_e32 v50, v50, v84
	v_sub_f32_e32 v51, v51, v84
	v_sub_f32_e32 v52, v52, v84
	v_sub_f32_e32 v53, v53, v84
	v_sub_f32_e32 v54, v54, v84
	v_sub_f32_e32 v55, v55, v84
	v_sub_f32_e32 v56, v56, v84
	v_sub_f32_e32 v57, v57, v84
	v_sub_f32_e32 v58, v58, v84
	v_sub_f32_e32 v59, v59, v84
	v_sub_f32_e32 v60, v60, v84
	v_sub_f32_e32 v61, v61, v84
	v_sub_f32_e32 v62, v62, v84
	v_sub_f32_e32 v63, v63, v84
	v_sub_f32_e32 v64, v64, v84
	v_sub_f32_e32 v65, v65, v84
	v_sub_f32_e32 v66, v66, v84
	v_sub_f32_e32 v67, v67, v84
	s_mov_b32 s56, 0x41000000
	s_branch .LBB0_1004
.Lrare_B:
	s_nop 0
	v_add_f32_e32 v210, v180, v36
	v_cvt_pk_bf16_f32 v210, v210, v210
	v_lshlrev_b32_e32 v210, 16, v210
	v_cndmask_b32_e32 v210, v180, v210, vcc
	v_sub_f32_e32 v36, v180, v210
	v_sub_f32_e32 v186, v210, v180
	v_xor_b32_e32 v250, 0x80000000, v210
	v_min_f32_e32 v36, 0, v36
	v_lshrrev_b32_e32 v250, 16, v250
	v_exp_f32_e32 v36, v36
	v_cndmask_b32_e64 v250, 0, v250, s[2:3]
	s_and_saveexec_b64 s[14:15], s[2:3]
	ds_write_b32 v202, v36
	s_or_b64 exec, exec, s[14:15]
	v_mul_f32_e32 v2, v2, v36
	ds_read_b32 v36, v1
	ds_read_b32 v37, v1 offset:4
	ds_read_b32 v38, v1 offset:8
	ds_read_b32 v39, v1 offset:12
	ds_read_b32 v40, v1 offset:32
	ds_read_b32 v41, v1 offset:36
	ds_read_b32 v42, v1 offset:40
	ds_read_b32 v43, v1 offset:44
	ds_read_b32 v44, v1 offset:64
	ds_read_b32 v45, v1 offset:68
	ds_read_b32 v46, v1 offset:72
	ds_read_b32 v47, v1 offset:76
	ds_read_b32 v48, v1 offset:96
	ds_read_b32 v49, v1 offset:100
	ds_read_b32 v50, v1 offset:104
	ds_read_b32 v51, v1 offset:108
	s_waitcnt lgkmcnt(0)
	v_pk_mul_f32 v[20:21], v[20:21], v[36:37]
	v_pk_mul_f32 v[22:23], v[22:23], v[38:39]
	v_pk_mul_f32 v[24:25], v[24:25], v[40:41]
	v_pk_mul_f32 v[26:27], v[26:27], v[42:43]
	v_pk_mul_f32 v[28:29], v[28:29], v[44:45]
	v_pk_mul_f32 v[30:31], v[30:31], v[46:47]
	v_pk_mul_f32 v[32:33], v[32:33], v[48:49]
	v_pk_mul_f32 v[34:35], v[34:35], v[50:51]
	v_pk_mul_f32 v[4:5], v[4:5], v[36:37]
	v_pk_mul_f32 v[6:7], v[6:7], v[38:39]
	v_pk_mul_f32 v[8:9], v[8:9], v[40:41]
	v_pk_mul_f32 v[10:11], v[10:11], v[42:43]
	v_pk_mul_f32 v[12:13], v[12:13], v[44:45]
	v_pk_mul_f32 v[14:15], v[14:15], v[46:47]
	v_pk_mul_f32 v[16:17], v[16:17], v[48:49]
	v_pk_mul_f32 v[18:19], v[18:19], v[50:51]
	v_sub_f32_e32 v68, v68, v186
	v_sub_f32_e32 v69, v69, v186
	v_sub_f32_e32 v70, v70, v186
	v_sub_f32_e32 v71, v71, v186
	v_sub_f32_e32 v72, v72, v186
	v_sub_f32_e32 v73, v73, v186
	v_sub_f32_e32 v74, v74, v186
	v_sub_f32_e32 v75, v75, v186
	v_sub_f32_e32 v76, v76, v186
	v_sub_f32_e32 v77, v77, v186
	v_sub_f32_e32 v78, v78, v186
	v_sub_f32_e32 v79, v79, v186
	v_sub_f32_e32 v80, v80, v186
	v_sub_f32_e32 v81, v81, v186
	v_sub_f32_e32 v82, v82, v186
	v_sub_f32_e32 v83, v83, v186
	v_sub_f32_e32 v84, v84, v186
	v_sub_f32_e32 v85, v85, v186
	v_sub_f32_e32 v86, v86, v186
	v_sub_f32_e32 v87, v87, v186
	v_sub_f32_e32 v88, v88, v186
	v_sub_f32_e32 v89, v89, v186
	v_sub_f32_e32 v90, v90, v186
	v_sub_f32_e32 v91, v91, v186
	v_sub_f32_e32 v92, v92, v186
	v_sub_f32_e32 v93, v93, v186
	v_sub_f32_e32 v94, v94, v186
	v_sub_f32_e32 v95, v95, v186
	v_sub_f32_e32 v96, v96, v186
	v_sub_f32_e32 v97, v97, v186
	v_sub_f32_e32 v98, v98, v186
	v_sub_f32_e32 v99, v99, v186
	s_mov_b32 s56, 0x41000000
	s_branch .LBB0_1009
